# MLA attention: first V-fragment LDS reads hoisted above the second half of the softmax exps (V fragment register sets swapped)
# baseline (speedup 1.0000x reference)
; #define PIN() do { asm volatile("" ::: "memory"); __builtin_amdgcn_sched_barrier(0); } while (0)
; #define MFMA(a, b, c) __builtin_amdgcn_mfma_f32_32x32x16_bf16((a), (b), (c), 0, 0, 0)
; DI unsigned pk2(float a, float b) { f32x2_t v = {a, b}; bf16x2_t r = __builtin_convertvector(v, bf16x2_t); return __builtin_bit_cast(unsigned, r); }
; #define VLD(dst_, s4_) do { _Pragma("unroll") for (int db = 0; db < 4; ++db) dst_[db].v = *(const bf16x8*)(vbase + db * 32 * VSTR + (s4_) * 32); } while (0)
; template <int DQK, int NM>
; DI void attn_item(const bf16_t* Qb, const bf16_t* Kb, size_t mstride, const bf16_t* VTb,
;                   int q0, int nkt, float cs, bf16_t* Orow  , float lam, float outscale, const float* subw, char* smem) {
;     ...
;     {
;       const f32x2_t cs2 = {cs, cs}, mc2 = {mrun * cs, mrun * cs};
;       f32x2_t ps2 = {0.f, 0.f};
; #pragma unroll
;       for (int kb = 0; kb < 2; ++kb)
; #pragma unroll
;         for (int i = 0; i < 16; i += 2) {
;           f32x2_t t = {sacc[kb][i], sacc[kb][i + 1]};
;           t = t * cs2 - mc2;
;           t.x = __builtin_amdgcn_exp2f(t.x); t.y = __builtin_amdgcn_exp2f(t.y);
;           sacc[kb][i] = t.x; sacc[kb][i + 1] = t.y;
;           ps2 = ps2 + t;
;         }
;       lrun += ps2.x + ps2.y;
;     }
;     const char* vbase = cur + KT_BYTES + l31 * VSTR + hh * 16;
;     {
;       struct VF { bf16x8 v; };
;       VF vfa[4], vfb[4];
;     ...
;       VLD(vfa, 0);
; #pragma unroll
;       for (int s4 = 0; s4 < 4; ++s4) {
;         const int kb = s4 >> 1, sp = s4 & 1;
;         PIN();
;         if (s4 < 3) { if (s4 & 1) VLD(vfa, s4 + 1); else VLD(vfb, s4 + 1); }
;         union { bf16x8 v; unsigned u[4]; } pf;
; #pragma unroll
;         for (int e = 0; e < 4; ++e) pf.u[e] = pk2(sacc[kb][8 * sp + 2 * e], sacc[kb][8 * sp + 2 * e + 1]);
;         PIN();
; #pragma unroll
;         for (int db = 0; db < 4; ++db) { if (s4 & 1) oacc[db] = MFMA(vfb[db].v, pf.v, oacc[db]); else oacc[db] = MFMA(vfa[db].v, pf.v, oacc[db]); }
;         {
;           char* b_ = smem + ((kt + 1) & 1) * BUF;
;           if (s4 == 0) { *(uint4*)(b_ + klo[0]) = kreg0; if (NKC > 2) *(uint4*)(b_ + klo[2]) = kreg2; }
;           if (s4 == 1) { *(uint4*)(b_ + klo[1]) = kreg1; }
;           if (s4 == 2) { *(uint4*)(b_ + vlo0) = vreg0; }
;           if (s4 == 3) { *(uint4*)(b_ + vlo1) = vreg1; }
;         }
;       }
;     ...
;     }
;     PIN();
;     __syncthreads();
.LBB0_126:
	v_mul_f32_e32 v196, 0x3dd53b95, v218
	v_fma_f32 v80, v80, s26, -v196
	v_fma_f32 v81, v81, s26, -v196
	v_fma_f32 v64, v64, s26, -v196
	v_fma_f32 v65, v65, s26, -v196
	v_exp_f32_e32 v220, v80
	v_exp_f32_e32 v221, v81
	v_fma_f32 v80, v82, s26, -v196
	v_fma_f32 v81, v83, s26, -v196
	v_fma_f32 v82, v88, s26, -v196
	v_fma_f32 v83, v89, s26, -v196
	v_exp_f32_e32 v222, v80
	v_exp_f32_e32 v223, v81
	v_fma_f32 v80, v84, s26, -v196
	v_fma_f32 v81, v85, s26, -v196
	v_exp_f32_e32 v228, v82
	v_exp_f32_e32 v224, v80
	v_exp_f32_e32 v225, v81
	v_fma_f32 v80, v86, s26, -v196
	v_fma_f32 v81, v87, s26, -v196
	v_exp_f32_e32 v229, v83
	v_exp_f32_e32 v226, v80
	v_exp_f32_e32 v227, v81
	v_fma_f32 v82, v90, s26, -v196
	v_fma_f32 v83, v91, s26, -v196
	v_exp_f32_e32 v230, v82
	v_exp_f32_e32 v231, v83
	v_fma_f32 v82, v92, s26, -v196
	v_fma_f32 v83, v93, s26, -v196
	v_exp_f32_e32 v232, v82
	v_exp_f32_e32 v233, v83
	v_fma_f32 v82, v94, s26, -v196
	v_fma_f32 v83, v95, s26, -v196
	v_exp_f32_e32 v234, v82
	v_exp_f32_e32 v235, v83
	v_add3_u32 v219, s25, v214, v170
	ds_read_b128 v[80:83], v219 offset:25600
	ds_read_b128 v[84:87], v219 offset:30208
	ds_read_b128 v[88:91], v219 offset:34816
	ds_read_b128 v[92:95], v219 offset:39424
	v_exp_f32_e32 v236, v64
	v_exp_f32_e32 v237, v65
	v_fma_f32 v64, v66, s26, -v196
	v_fma_f32 v65, v67, s26, -v196
	v_exp_f32_e32 v238, v64
	v_exp_f32_e32 v239, v65
	v_fma_f32 v64, v68, s26, -v196
	v_fma_f32 v65, v69, s26, -v196
	v_exp_f32_e32 v240, v64
	v_exp_f32_e32 v241, v65
	v_fma_f32 v64, v70, s26, -v196
	v_fma_f32 v65, v71, s26, -v196
	v_exp_f32_e32 v242, v64
	v_exp_f32_e32 v243, v65
	v_fma_f32 v66, v72, s26, -v196
	v_fma_f32 v67, v73, s26, -v196
	v_exp_f32_e32 v244, v66
	v_exp_f32_e32 v245, v67
	v_fma_f32 v66, v74, s26, -v196
	v_fma_f32 v67, v75, s26, -v196
	v_exp_f32_e32 v246, v66
	v_exp_f32_e32 v247, v67
	v_fma_f32 v66, v76, s26, -v196
	v_fma_f32 v67, v77, s26, -v196
	v_exp_f32_e32 v248, v66
	v_exp_f32_e32 v249, v67
	v_fma_f32 v66, v78, s26, -v196
	v_fma_f32 v67, v79, s26, -v196
	v_exp_f32_e32 v250, v66
	v_exp_f32_e32 v251, v67
	s_cmp_eq_u32 s24, 1
	s_cselect_b32 s24, 0xac00, 0
	s_add_i32 s24, s24, 0
	v_add_u32_e32 v206, s24, v197
	v_add_u32_e32 v211, s24, v216
	ds_read_b128 v[64:67], v219 offset:25632
	ds_read_b128 v[68:71], v219 offset:30240
	ds_read_b128 v[72:75], v219 offset:34848
	ds_read_b128 v[76:79], v219 offset:39456
	v_add_f32_e32 v203, v220, v221
	v_add_f32_e32 v203, v222, v203
	v_add_f32_e32 v203, v223, v203
	v_add_f32_e32 v203, v224, v203
	v_add_f32_e32 v203, v225, v203
	v_add_f32_e32 v203, v226, v203
	v_add_f32_e32 v203, v227, v203
	v_cvt_pk_bf16_f32 v220, v220, v221
	v_cvt_pk_bf16_f32 v221, v222, v223
	v_cvt_pk_bf16_f32 v222, v224, v225
	v_cvt_pk_bf16_f32 v223, v226, v227
	s_waitcnt lgkmcnt(7)
	s_nop 0
	v_mfma_f32_32x32x16_bf16 v[32:47], v[80:83], v[220:223], v[32:47]
	v_add_f32_e32 v203, v228, v203
	v_add_f32_e32 v203, v229, v203
	s_waitcnt vmcnt(4)
	ds_write_b128 v206, v[158:161]
	s_waitcnt vmcnt(2)
	ds_write_b128 v211, v[162:165]
	s_waitcnt lgkmcnt(8)
	v_mfma_f32_32x32x16_bf16 v[48:63], v[84:87], v[220:223], v[48:63]
	v_add_f32_e32 v203, v230, v203
	v_add_f32_e32 v203, v231, v203
	s_waitcnt lgkmcnt(7)
	v_mfma_f32_32x32x16_bf16 v[16:31], v[88:91], v[220:223], v[16:31]
	v_add_f32_e32 v203, v232, v203
	v_add_f32_e32 v203, v233, v203
	s_waitcnt lgkmcnt(6)
	v_mfma_f32_32x32x16_bf16 v[0:15], v[92:95], v[220:223], v[0:15]
	v_add_f32_e32 v203, v234, v203
	v_add_f32_e32 v203, v235, v203
	ds_read_b128 v[80:83], v219 offset:25664
	ds_read_b128 v[84:87], v219 offset:30272
	ds_read_b128 v[88:91], v219 offset:34880
	ds_read_b128 v[92:95], v219 offset:39488
	v_cvt_pk_bf16_f32 v158, v228, v229
	v_cvt_pk_bf16_f32 v159, v230, v231
	v_cvt_pk_bf16_f32 v160, v232, v233
	v_cvt_pk_bf16_f32 v161, v234, v235
	s_waitcnt lgkmcnt(9)
	s_nop 0
	v_mfma_f32_32x32x16_bf16 v[32:47], v[64:67], v[158:161], v[32:47]
	v_add_f32_e32 v203, v236, v203
	v_add_f32_e32 v203, v237, v203
	v_add_u32_e32 v64, s24, v215
	ds_write_b128 v64, v[154:157]
	s_waitcnt lgkmcnt(9)
	v_mfma_f32_32x32x16_bf16 v[48:63], v[68:71], v[158:161], v[48:63]
	v_add_f32_e32 v203, v238, v203
	v_add_f32_e32 v203, v239, v203
	s_waitcnt lgkmcnt(8)
	v_mfma_f32_32x32x16_bf16 v[16:31], v[72:75], v[158:161], v[16:31]
	v_add_f32_e32 v203, v240, v203
	v_add_f32_e32 v203, v241, v203
	s_waitcnt lgkmcnt(7)
	v_mfma_f32_32x32x16_bf16 v[0:15], v[76:79], v[158:161], v[0:15]
	v_add_f32_e32 v203, v242, v203
	v_add_f32_e32 v203, v243, v203
	ds_read_b128 v[64:67], v219 offset:25696
	ds_read_b128 v[68:71], v219 offset:30304
	ds_read_b128 v[72:75], v219 offset:34912
	ds_read_b128 v[76:79], v219 offset:39520
	v_cvt_pk_bf16_f32 v154, v236, v237
	v_cvt_pk_bf16_f32 v155, v238, v239
	v_cvt_pk_bf16_f32 v156, v240, v241
	v_cvt_pk_bf16_f32 v157, v242, v243
	s_waitcnt lgkmcnt(8)
	s_nop 0
	v_mfma_f32_32x32x16_bf16 v[32:47], v[80:83], v[154:157], v[32:47]
	v_add_f32_e32 v203, v244, v203
	v_add_f32_e32 v203, v245, v203
	v_add_u32_e32 v80, s24, v182
	s_waitcnt vmcnt(1)
	ds_write_b128 v80, v[150:153] offset:25600
	s_waitcnt lgkmcnt(8)
	v_mfma_f32_32x32x16_bf16 v[48:63], v[84:87], v[154:157], v[48:63]
	v_add_f32_e32 v203, v246, v203
	v_add_f32_e32 v203, v247, v203
	s_waitcnt lgkmcnt(7)
	v_mfma_f32_32x32x16_bf16 v[16:31], v[88:91], v[154:157], v[16:31]
	v_add_f32_e32 v203, v248, v203
	v_add_f32_e32 v203, v249, v203
	s_waitcnt lgkmcnt(6)
	v_mfma_f32_32x32x16_bf16 v[0:15], v[92:95], v[154:157], v[0:15]
	v_add_f32_e32 v203, v250, v203
	v_add_f32_e32 v203, v251, v203
	v_cvt_pk_bf16_f32 v80, v244, v245
	v_cvt_pk_bf16_f32 v81, v246, v247
	v_cvt_pk_bf16_f32 v82, v248, v249
	v_cvt_pk_bf16_f32 v83, v250, v251
	s_waitcnt lgkmcnt(4)
	s_nop 0
	v_mfma_f32_32x32x16_bf16 v[32:47], v[64:67], v[80:83], v[32:47]
	v_add_u32_e32 v84, s24, v184
	s_waitcnt vmcnt(0)
	ds_write_b128 v84, v[146:149] offset:25600
	v_add_f32_e32 v185, v185, v203
	s_waitcnt lgkmcnt(4)
	v_mfma_f32_32x32x16_bf16 v[48:63], v[68:71], v[80:83], v[48:63]
	s_waitcnt lgkmcnt(3)
	v_mfma_f32_32x32x16_bf16 v[16:31], v[72:75], v[80:83], v[16:31]
	s_waitcnt lgkmcnt(2)
	v_mfma_f32_32x32x16_bf16 v[0:15], v[76:79], v[80:83], v[0:15]
	s_mov_b64 s[34:35], 0x80
	s_add_i32 s37, s37, 1
	v_lshl_add_u64 v[186:187], v[186:187], 0, s[34:35]
	v_lshl_add_u64 v[188:189], v[188:189], 0, s[34:35]
	s_mov_b64 s[34:35], 0x6000
	v_lshl_add_u64 v[190:191], v[190:191], 0, s[34:35]
	v_lshl_add_u64 v[192:193], v[192:193], 0, s[34:35]
	s_cmpk_eq_i32 s37, 0x84
	v_lshl_add_u64 v[194:195], v[194:195], 0, s[34:35]
	s_waitcnt lgkmcnt(0)
	s_barrier
	s_cbranch_scc1 .LBB0_129
